# speedup vs baseline: 1.0118x; 1.0118x over previous
.LBB0_95:
	s_or_b64 exec, exec, s[4:5]
	s_mov_b32 s6, -1
	s_add_i32 s4, s52, 0xfffff000
	v_mbcnt_lo_u32_b32 v128, s6, 0
	v_mbcnt_hi_u32_b32 v128, s6, v128
	v_add_u32_e32 v130, s43, v128
	s_ashr_i32 s4, s4, 10
	s_cmp_gt_i32 s61, 15
	v_lshrrev_b32_e32 v128, 1, v130
	v_ashrrev_i32_e32 v131, 2, v130
	v_and_b32_e32 v128, 0x60, v128
	v_lshrrev_b32_e32 v129, 2, v130
	v_and_b32_e32 v131, 0xffffffc0, v131
	v_and_or_b32 v130, v130, 15, s52
	s_cselect_b32 s4, s4, 8
	v_readlane_b32 s5, v255, 8
	v_and_or_b32 v162, v129, 12, v128
	v_add_u32_e32 v130, v130, v131
	s_add_i32 s4, s4, s5
	v_readlane_b32 s44, v253, 1
	v_or_b32_e32 v148, s53, v162
	v_ashrrev_i32_e32 v131, 31, v130
	s_mul_hi_i32 s5, s4, 0xc000
	s_mul_i32 s4, s4, 0xc000
	v_readlane_b32 s50, v253, 7
	v_ashrrev_i32_e32 v149, 31, v148
	v_readlane_b32 s6, v253, 54
	v_lshlrev_b64 v[136:137], 13, v[130:131]
	v_or_b32_e32 v138, 16, v130
	v_or_b32_e32 v140, 32, v130
	v_or_b32_e32 v142, 48, v130
	v_add_u32_e32 v144, 0x80, v130
	v_add_u32_e32 v146, 0x90, v130
	v_add_u32_e32 v150, 0xa0, v130
	v_add_u32_e32 v130, 0xb0, v130
	v_readlane_b32 s51, v253, 8
	s_add_u32 s4, s50, s4
	v_lshlrev_b64 v[132:133], 2, v[148:149]
	v_readlane_b32 s7, v253, 55
	v_ashrrev_i32_e32 v151, 31, v150
	v_ashrrev_i32_e32 v131, 31, v130
	s_addc_u32 s5, s51, s5
	v_lshl_add_u64 v[134:135], s[6:7], 0, v[132:133]
	v_ashrrev_i32_e32 v139, 31, v138
	v_ashrrev_i32_e32 v141, 31, v140
	v_ashrrev_i32_e32 v143, 31, v142
	v_ashrrev_i32_e32 v145, 31, v144
	v_ashrrev_i32_e32 v147, 31, v146
	v_lshlrev_b64 v[150:151], 13, v[150:151]
	v_lshlrev_b64 v[152:153], 13, v[130:131]
	v_or_b32_e32 v130, 16, v148
	s_add_u32 s4, s4, 0x2f76a000
	v_lshlrev_b64 v[138:139], 13, v[138:139]
	v_lshlrev_b64 v[140:141], 13, v[140:141]
	v_lshlrev_b64 v[142:143], 13, v[142:143]
	v_lshlrev_b64 v[144:145], 13, v[144:145]
	v_lshlrev_b64 v[146:147], 13, v[146:147]
	v_lshl_add_u64 v[202:203], v[134:135], 0, v[150:151]
	v_ashrrev_i32_e32 v131, 31, v130
	v_lshl_add_u64 v[216:217], s[6:7], 0, v[150:151]
	v_or_b32_e32 v150, s60, v162
	v_or_b32_e32 v148, 0x90, v148
	s_addc_u32 s5, s5, 0
	v_lshl_add_u64 v[184:185], v[134:135], 0, v[136:137]
	v_lshl_add_u64 v[186:187], v[134:135], 0, v[138:139]
	v_lshl_add_u64 v[188:189], v[134:135], 0, v[140:141]
	v_lshl_add_u64 v[190:191], v[134:135], 0, v[142:143]
	v_lshl_add_u64 v[192:193], v[134:135], 0, v[144:145]
	v_lshl_add_u64 v[194:195], v[134:135], 0, v[146:147]
	v_lshl_add_u64 v[204:205], v[134:135], 0, v[152:153]
	v_lshlrev_b64 v[134:135], 2, v[130:131]
	v_ashrrev_i32_e32 v151, 31, v150
	v_ashrrev_i32_e32 v149, 31, v148
	v_lshl_add_u64 v[212:213], s[4:5], 0, v[134:135]
	v_lshl_add_u64 v[154:155], s[6:7], 0, v[136:137]
	v_lshl_add_u64 v[156:157], s[6:7], 0, v[138:139]
	v_lshl_add_u64 v[158:159], s[6:7], 0, v[140:141]
	v_lshl_add_u64 v[160:161], s[6:7], 0, v[142:143]
	v_lshl_add_u64 v[164:165], s[6:7], 0, v[144:145]
	v_lshl_add_u64 v[214:215], s[6:7], 0, v[146:147]
	v_lshl_add_u64 v[218:219], s[6:7], 0, v[152:153]
	v_lshlrev_b64 v[150:151], 2, v[150:151]
	v_lshlrev_b64 v[230:231], 2, v[148:149]
	v_lshl_add_u64 v[128:129], s[4:5], 0, v[132:133]
	v_lshl_add_u64 v[130:131], v[154:155], 0, v[134:135]
	v_lshl_add_u64 v[206:207], v[156:157], 0, v[134:135]
	v_lshl_add_u64 v[208:209], v[158:159], 0, v[134:135]
	v_lshl_add_u64 v[210:211], v[160:161], 0, v[134:135]
	v_lshl_add_u64 v[220:221], v[164:165], 0, v[134:135]
	v_lshl_add_u64 v[222:223], v[214:215], 0, v[134:135]
	v_lshl_add_u64 v[224:225], v[216:217], 0, v[134:135]
	v_lshl_add_u64 v[228:229], v[218:219], 0, v[134:135]
	v_lshl_add_u64 v[146:147], v[154:155], 0, v[132:133]
	v_lshl_add_u64 v[144:145], v[156:157], 0, v[132:133]
	v_lshl_add_u64 v[142:143], v[158:159], 0, v[132:133]
	v_lshl_add_u64 v[140:141], v[160:161], 0, v[132:133]
	v_lshl_add_u64 v[138:139], v[164:165], 0, v[132:133]
	v_lshl_add_u64 v[136:137], v[214:215], 0, v[132:133]
	v_lshl_add_u64 v[134:135], v[216:217], 0, v[132:133]
	v_lshl_add_u64 v[132:133], v[218:219], 0, v[132:133]
	v_lshl_add_u64 v[180:181], s[4:5], 0, v[150:151]
	v_lshl_add_u64 v[166:167], v[154:155], 0, v[150:151]
	v_lshl_add_u64 v[168:169], v[156:157], 0, v[150:151]
	v_lshl_add_u64 v[170:171], v[158:159], 0, v[150:151]
	v_lshl_add_u64 v[172:173], v[160:161], 0, v[150:151]
	v_lshl_add_u64 v[174:175], v[164:165], 0, v[150:151]
	v_lshl_add_u64 v[176:177], v[214:215], 0, v[150:151]
	v_lshl_add_u64 v[178:179], v[216:217], 0, v[150:151]
	v_lshl_add_u64 v[182:183], v[218:219], 0, v[150:151]
	v_lshl_add_u64 v[148:149], v[154:155], 0, v[230:231]
	v_lshl_add_u64 v[150:151], v[156:157], 0, v[230:231]
	v_lshl_add_u64 v[152:153], v[158:159], 0, v[230:231]
	v_lshl_add_u64 v[154:155], v[160:161], 0, v[230:231]
	v_lshl_add_u64 v[156:157], v[164:165], 0, v[230:231]
	v_lshl_add_u64 v[158:159], v[214:215], 0, v[230:231]
	v_lshl_add_u64 v[160:161], v[216:217], 0, v[230:231]
	v_lshl_add_u64 v[164:165], v[218:219], 0, v[230:231]
	v_lshl_add_u64 v[162:163], s[4:5], 0, v[230:231]
	v_readlane_b32 s45, v253, 2
	v_readlane_b32 s46, v253, 3
	v_readlane_b32 s47, v253, 4
	v_readlane_b32 s48, v253, 5
	v_readlane_b32 s49, v253, 6
	global_load_dwordx4 v[128:131], v[128:129], off
	global_load_dwordx4 v[212:215], v[212:213], off
	global_load_dwordx4 v[180:183], v[180:181], off
	global_load_dwordx4 v[160:163], v[162:163], off
	global_load_dwordx4 v[148:151], v[146:147], off
	global_load_dwordx4 v[152:155], v[144:145], off
	global_load_dwordx4 v[156:159], v[142:143], off
	global_load_dwordx4 v[164:167], v[140:141], off
	global_load_dwordx4 v[168:171], v[138:139], off
	global_load_dwordx4 v[172:175], v[136:137], off
	global_load_dwordx4 v[176:179], v[134:135], off
	global_load_dwordx4 v[184:187], v[132:133], off
	global_load_dwordx4 v[188:191], v[146:147], off offset:64
	global_load_dwordx4 v[192:195], v[144:145], off offset:64
	global_load_dwordx4 v[204:207], v[142:143], off offset:64
	global_load_dwordx4 v[208:211], v[140:141], off offset:64
	global_load_dwordx4 v[216:219], v[138:139], off offset:64
	global_load_dwordx4 v[220:223], v[136:137], off offset:64
	global_load_dwordx4 v[228:231], v[134:135], off offset:64
	global_load_dwordx4 v[232:235], v[132:133], off offset:64
	s_waitcnt vmcnt(8)
	v_pk_fma_f32 v[52:53], v[52:53], v[128:129], v[148:149]
	v_pk_fma_f32 v[54:55], v[54:55], v[130:131], v[150:151]
	v_pk_fma_f32 v[68:69], v[68:69], v[128:129], v[152:153]
	v_pk_fma_f32 v[70:71], v[70:71], v[130:131], v[154:155]
	v_pk_fma_f32 v[76:77], v[76:77], v[128:129], v[156:157]
	v_pk_fma_f32 v[78:79], v[78:79], v[130:131], v[158:159]
	v_pk_fma_f32 v[84:85], v[84:85], v[128:129], v[164:165]
	v_pk_fma_f32 v[86:87], v[86:87], v[130:131], v[166:167]
	v_pk_fma_f32 v[100:101], v[100:101], v[128:129], v[168:169]
	v_pk_fma_f32 v[102:103], v[102:103], v[130:131], v[170:171]
	v_pk_fma_f32 v[112:113], v[112:113], v[128:129], v[172:173]
	v_pk_fma_f32 v[114:115], v[114:115], v[130:131], v[174:175]
	v_pk_fma_f32 v[120:121], v[120:121], v[128:129], v[176:177]
	v_pk_fma_f32 v[122:123], v[122:123], v[130:131], v[178:179]
	v_pk_fma_f32 v[124:125], v[124:125], v[128:129], v[184:185]
	v_pk_fma_f32 v[126:127], v[126:127], v[130:131], v[186:187]
	global_store_dwordx4 v[146:147], v[52:55], off
	global_store_dwordx4 v[144:145], v[68:71], off
	global_store_dwordx4 v[142:143], v[76:79], off
	global_store_dwordx4 v[140:141], v[84:87], off
	global_store_dwordx4 v[138:139], v[100:103], off
	global_store_dwordx4 v[136:137], v[112:115], off
	global_store_dwordx4 v[134:135], v[120:123], off
	global_store_dwordx4 v[132:133], v[124:127], off
	global_load_dwordx4 v[148:151], v[146:147], off offset:512
	global_load_dwordx4 v[152:155], v[144:145], off offset:512
	global_load_dwordx4 v[156:159], v[142:143], off offset:512
	global_load_dwordx4 v[164:167], v[140:141], off offset:512
	global_load_dwordx4 v[168:171], v[138:139], off offset:512
	global_load_dwordx4 v[172:175], v[136:137], off offset:512
	global_load_dwordx4 v[176:179], v[134:135], off offset:512
	global_load_dwordx4 v[184:187], v[132:133], off offset:512
	s_waitcnt vmcnt(16)
	v_pk_fma_f32 v[104:105], v[104:105], v[212:213], v[188:189]
	v_pk_fma_f32 v[106:107], v[106:107], v[214:215], v[190:191]
	v_pk_fma_f32 v[116:117], v[116:117], v[212:213], v[192:193]
	v_pk_fma_f32 v[118:119], v[118:119], v[214:215], v[194:195]
	v_pk_fma_f32 v[108:109], v[108:109], v[212:213], v[204:205]
	v_pk_fma_f32 v[110:111], v[110:111], v[214:215], v[206:207]
	v_pk_fma_f32 v[96:97], v[96:97], v[212:213], v[208:209]
	v_pk_fma_f32 v[98:99], v[98:99], v[214:215], v[210:211]
	v_pk_fma_f32 v[92:93], v[92:93], v[212:213], v[216:217]
	v_pk_fma_f32 v[94:95], v[94:95], v[214:215], v[218:219]
	v_pk_fma_f32 v[88:89], v[88:89], v[212:213], v[220:221]
	v_pk_fma_f32 v[90:91], v[90:91], v[214:215], v[222:223]
	v_pk_fma_f32 v[80:81], v[80:81], v[212:213], v[228:229]
	v_pk_fma_f32 v[82:83], v[82:83], v[214:215], v[230:231]
	v_pk_fma_f32 v[72:73], v[72:73], v[212:213], v[232:233]
	v_pk_fma_f32 v[74:75], v[74:75], v[214:215], v[234:235]
	global_store_dwordx4 v[146:147], v[104:107], off offset:64
	global_store_dwordx4 v[144:145], v[116:119], off offset:64
	global_store_dwordx4 v[142:143], v[108:111], off offset:64
	global_store_dwordx4 v[140:141], v[96:99], off offset:64
	global_store_dwordx4 v[138:139], v[92:95], off offset:64
	global_store_dwordx4 v[136:137], v[88:91], off offset:64
	global_store_dwordx4 v[134:135], v[80:83], off offset:64
	global_store_dwordx4 v[132:133], v[72:75], off offset:64
	global_load_dwordx4 v[188:191], v[146:147], off offset:576
	global_load_dwordx4 v[192:195], v[144:145], off offset:576
	global_load_dwordx4 v[204:207], v[142:143], off offset:576
	global_load_dwordx4 v[208:211], v[140:141], off offset:576
	global_load_dwordx4 v[216:219], v[138:139], off offset:576
	global_load_dwordx4 v[220:223], v[136:137], off offset:576
	global_load_dwordx4 v[228:231], v[134:135], off offset:576
	global_load_dwordx4 v[232:235], v[132:133], off offset:576
	s_waitcnt vmcnt(16)
	v_pk_fma_f32 v[28:29], v[28:29], v[180:181], v[148:149]
	v_pk_fma_f32 v[30:31], v[30:31], v[182:183], v[150:151]
	v_pk_fma_f32 v[36:37], v[36:37], v[180:181], v[152:153]
	v_pk_fma_f32 v[38:39], v[38:39], v[182:183], v[154:155]
	v_pk_fma_f32 v[40:41], v[40:41], v[180:181], v[156:157]
	v_pk_fma_f32 v[42:43], v[42:43], v[182:183], v[158:159]
	v_pk_fma_f32 v[44:45], v[44:45], v[180:181], v[164:165]
	v_pk_fma_f32 v[46:47], v[46:47], v[182:183], v[166:167]
	v_pk_fma_f32 v[48:49], v[48:49], v[180:181], v[168:169]
	v_pk_fma_f32 v[50:51], v[50:51], v[182:183], v[170:171]
	v_pk_fma_f32 v[56:57], v[56:57], v[180:181], v[172:173]
	v_pk_fma_f32 v[58:59], v[58:59], v[182:183], v[174:175]
	v_pk_fma_f32 v[60:61], v[60:61], v[180:181], v[176:177]
	v_pk_fma_f32 v[62:63], v[62:63], v[182:183], v[178:179]
	v_pk_fma_f32 v[64:65], v[64:65], v[180:181], v[184:185]
	v_pk_fma_f32 v[66:67], v[66:67], v[182:183], v[186:187]
	global_store_dwordx4 v[146:147], v[28:31], off offset:512
	global_store_dwordx4 v[144:145], v[36:39], off offset:512
	global_store_dwordx4 v[142:143], v[40:43], off offset:512
	global_store_dwordx4 v[140:141], v[44:47], off offset:512
	global_store_dwordx4 v[138:139], v[48:51], off offset:512
	global_store_dwordx4 v[136:137], v[56:59], off offset:512
	global_store_dwordx4 v[134:135], v[60:63], off offset:512
	global_store_dwordx4 v[132:133], v[64:67], off offset:512
	s_waitcnt vmcnt(8)
	v_pk_fma_f32 v[0:1], v[0:1], v[160:161], v[188:189]
	v_pk_fma_f32 v[2:3], v[2:3], v[162:163], v[190:191]
	v_pk_fma_f32 v[4:5], v[4:5], v[160:161], v[192:193]
	v_pk_fma_f32 v[6:7], v[6:7], v[162:163], v[194:195]
	v_pk_fma_f32 v[8:9], v[8:9], v[160:161], v[204:205]
	v_pk_fma_f32 v[10:11], v[10:11], v[162:163], v[206:207]
	v_pk_fma_f32 v[12:13], v[12:13], v[160:161], v[208:209]
	v_pk_fma_f32 v[14:15], v[14:15], v[162:163], v[210:211]
	v_pk_fma_f32 v[16:17], v[16:17], v[160:161], v[216:217]
	v_pk_fma_f32 v[18:19], v[18:19], v[162:163], v[218:219]
	v_pk_fma_f32 v[20:21], v[20:21], v[160:161], v[220:221]
	v_pk_fma_f32 v[22:23], v[22:23], v[162:163], v[222:223]
	v_pk_fma_f32 v[24:25], v[24:25], v[160:161], v[228:229]
	v_pk_fma_f32 v[26:27], v[26:27], v[162:163], v[230:231]
	v_pk_fma_f32 v[32:33], v[32:33], v[160:161], v[232:233]
	v_pk_fma_f32 v[34:35], v[34:35], v[162:163], v[234:235]
	global_store_dwordx4 v[146:147], v[0:3], off offset:576
	global_store_dwordx4 v[144:145], v[4:7], off offset:576
	global_store_dwordx4 v[142:143], v[8:11], off offset:576
	global_store_dwordx4 v[140:141], v[12:15], off offset:576
	global_store_dwordx4 v[138:139], v[16:19], off offset:576
	global_store_dwordx4 v[136:137], v[20:23], off offset:576
	global_store_dwordx4 v[134:135], v[24:27], off offset:576
	global_store_dwordx4 v[132:133], v[32:35], off offset:576

.LBB0_212:
	s_or_b64 exec, exec, s[28:29]
	s_cmp_lt_i32 s52, 16
	s_cselect_b64 s[36:37], -1, 0
	s_add_i32 s9, s10, 0xfffff000
	s_ashr_i32 s9, s9, 10
	s_and_b64 s[28:29], s[36:37], exec
	s_mov_b32 s28, -1
	s_cselect_b32 s9, 8, s9
	v_mbcnt_lo_u32_b32 v128, s28, 0
	v_mbcnt_hi_u32_b32 v128, s28, v128
	v_add_u32_e32 v134, s43, v128
	v_readlane_b32 s11, v255, 8
	v_lshrrev_b32_e32 v128, 1, v134
	v_and_b32_e32 v128, 0x60, v128
	v_lshrrev_b32_e32 v129, 2, v134
	v_and_or_b32 v196, v129, 12, v128
	v_or_b32_e32 v130, s6, v196
	v_ashrrev_i32_e32 v131, 31, v130
	v_lshlrev_b64 v[132:133], 2, v[130:131]
	v_ashrrev_i32_e32 v131, 2, v134
	v_and_b32_e32 v131, 0xffffffc0, v131
	v_and_or_b32 v134, v134, 15, s10
	v_add_u32_e32 v134, v134, v131
	v_or_b32_e32 v138, 16, v134
	v_ashrrev_i32_e32 v139, 31, v138
	s_add_i32 s9, s9, s11
	v_readlane_b32 s44, v253, 1
	v_lshlrev_b64 v[168:169], 13, v[138:139]
	v_or_b32_e32 v138, 32, v134
	s_mul_hi_i32 s11, s9, 0xc000
	s_mul_i32 s9, s9, 0xc000
	v_readlane_b32 s50, v253, 7
	v_ashrrev_i32_e32 v139, 31, v138
	v_readlane_b32 s51, v253, 8
	s_add_u32 s9, s50, s9
	v_lshlrev_b64 v[170:171], 13, v[138:139]
	v_or_b32_e32 v138, 48, v134
	s_addc_u32 s11, s51, s11
	v_ashrrev_i32_e32 v139, 31, v138
	s_add_u32 s28, s9, 0x2f764000
	v_lshlrev_b64 v[172:173], 13, v[138:139]
	v_add_u32_e32 v138, 0x80, v134
	s_addc_u32 s29, s11, 0
	v_ashrrev_i32_e32 v139, 31, v138
	s_and_b64 s[36:37], s[36:37], exec
	v_lshlrev_b64 v[174:175], 13, v[138:139]
	v_add_u32_e32 v138, 0x90, v134
	v_readlane_b32 s36, v255, 4
	v_ashrrev_i32_e32 v135, 31, v134
	v_ashrrev_i32_e32 v139, 31, v138
	v_readlane_b32 s9, v254, 16
	v_readlane_b32 s11, v254, 17
	v_readlane_b32 s37, v255, 5
	v_lshlrev_b64 v[164:165], 13, v[134:135]
	v_lshlrev_b64 v[176:177], 13, v[138:139]
	v_add_u32_e32 v138, 0xa0, v134
	v_add_u32_e32 v134, 0xb0, v134
	s_cselect_b32 s9, s12, s9
	s_cselect_b32 s11, s13, s11
	s_and_b64 s[36:37], s[36:37], exec
	v_ashrrev_i32_e32 v135, 31, v134
	v_readlane_b32 s36, v253, 54
	v_lshlrev_b64 v[182:183], 13, v[134:135]
	v_or_b32_e32 v134, 16, v130
	v_readlane_b32 s37, v253, 55
	v_ashrrev_i32_e32 v135, 31, v134
	v_lshl_add_u64 v[184:185], v[134:135], 2, s[28:29]
	v_lshl_add_u64 v[134:135], s[36:37], 0, v[164:165]
	v_lshl_add_u64 v[146:147], v[134:135], 0, v[132:133]
	v_lshl_add_u64 v[134:135], s[36:37], 0, v[168:169]
	v_lshl_add_u64 v[144:145], v[134:135], 0, v[132:133]
	v_lshl_add_u64 v[134:135], s[36:37], 0, v[170:171]
	v_lshl_add_u64 v[142:143], v[134:135], 0, v[132:133]
	v_lshl_add_u64 v[134:135], s[36:37], 0, v[172:173]
	s_cselect_b32 s57, s11, s37
	s_cselect_b32 s56, s9, s36
	v_ashrrev_i32_e32 v139, 31, v138
	v_lshl_add_u64 v[140:141], v[134:135], 0, v[132:133]
	v_lshl_add_u64 v[134:135], s[36:37], 0, v[174:175]
	v_lshl_add_u64 v[136:137], s[56:57], 0, v[132:133]
	v_lshlrev_b64 v[178:179], 13, v[138:139]
	v_lshl_add_u64 v[138:139], v[134:135], 0, v[132:133]
	v_lshl_add_u64 v[134:135], s[36:37], 0, v[176:177]
	v_lshl_add_u64 v[148:149], v[136:137], 0, v[164:165]
	v_lshl_add_u64 v[150:151], v[136:137], 0, v[168:169]
	v_lshl_add_u64 v[152:153], v[136:137], 0, v[170:171]
	v_lshl_add_u64 v[154:155], v[136:137], 0, v[172:173]
	v_lshl_add_u64 v[156:157], v[136:137], 0, v[174:175]
	v_lshl_add_u64 v[158:159], v[136:137], 0, v[176:177]
	v_lshl_add_u64 v[160:161], v[136:137], 0, v[178:179]
	v_lshl_add_u64 v[162:163], v[136:137], 0, v[182:183]
	v_lshl_add_u64 v[136:137], v[134:135], 0, v[132:133]
	v_lshl_add_u64 v[134:135], s[36:37], 0, v[178:179]
	v_lshl_add_u64 v[166:167], s[36:37], 0, v[182:183]
	v_lshl_add_u64 v[128:129], s[28:29], 0, v[132:133]
	v_lshl_add_u64 v[134:135], v[134:135], 0, v[132:133]
	v_lshl_add_u64 v[132:133], v[166:167], 0, v[132:133]
	v_or_b32_e32 v166, s8, v196
	v_ashrrev_i32_e32 v167, 31, v166
	v_lshl_add_u64 v[180:181], v[166:167], 2, s[28:29]
	v_lshl_add_u64 v[166:167], v[196:197], 0, s[6:7]
	v_lshl_add_u64 v[186:187], v[166:167], 2, s[56:57]
	v_lshl_add_u64 v[166:167], v[186:187], 0, v[164:165]
	v_lshl_add_u64 v[168:169], v[186:187], 0, v[168:169]
	v_lshl_add_u64 v[170:171], v[186:187], 0, v[170:171]
	v_lshl_add_u64 v[172:173], v[186:187], 0, v[172:173]
	v_lshl_add_u64 v[174:175], v[186:187], 0, v[174:175]
	v_lshl_add_u64 v[176:177], v[186:187], 0, v[176:177]
	v_lshl_add_u64 v[178:179], v[186:187], 0, v[178:179]
	v_lshl_add_u64 v[182:183], v[186:187], 0, v[182:183]
	v_or_b32_e32 v130, 0x90, v130
	v_ashrrev_i32_e32 v131, 31, v130
	v_lshl_add_u64 v[164:165], v[130:131], 2, s[28:29]
	v_readlane_b32 s45, v253, 2
	v_readlane_b32 s46, v253, 3
	v_readlane_b32 s47, v253, 4
	v_readlane_b32 s48, v253, 5
	v_readlane_b32 s49, v253, 6
	global_load_dwordx4 v[128:131], v[128:129], off
	global_load_dwordx4 v[184:187], v[184:185], off
	global_load_dwordx4 v[180:183], v[180:181], off
	global_load_dwordx4 v[164:167], v[164:165], off
	global_load_dwordx4 v[168:171], v[148:149], off
	global_load_dwordx4 v[172:175], v[150:151], off
	global_load_dwordx4 v[176:179], v[152:153], off
	global_load_dwordx4 v[188:191], v[154:155], off
	global_load_dwordx4 v[192:195], v[156:157], off
	global_load_dwordx4 v[204:207], v[158:159], off
	global_load_dwordx4 v[208:211], v[160:161], off
	global_load_dwordx4 v[212:215], v[162:163], off
	global_load_dwordx4 v[216:219], v[148:149], off offset:64
	global_load_dwordx4 v[220:223], v[150:151], off offset:64
	global_load_dwordx4 v[228:231], v[152:153], off offset:64
	global_load_dwordx4 v[232:235], v[154:155], off offset:64
	global_load_dwordx4 v[236:239], v[156:157], off offset:64
	global_load_dwordx4 v[240:243], v[158:159], off offset:64
	global_load_dwordx4 v[244:247], v[160:161], off offset:64
	global_load_dwordx4 v[248:251], v[162:163], off offset:64
	s_waitcnt vmcnt(8)
	v_pk_fma_f32 v[52:53], v[52:53], v[128:129], v[168:169]
	v_pk_fma_f32 v[54:55], v[54:55], v[130:131], v[170:171]
	v_pk_fma_f32 v[72:73], v[72:73], v[128:129], v[172:173]
	v_pk_fma_f32 v[74:75], v[74:75], v[130:131], v[174:175]
	v_pk_fma_f32 v[80:81], v[80:81], v[128:129], v[176:177]
	v_pk_fma_f32 v[82:83], v[82:83], v[130:131], v[178:179]
	v_pk_fma_f32 v[88:89], v[88:89], v[128:129], v[188:189]
	v_pk_fma_f32 v[90:91], v[90:91], v[130:131], v[190:191]
	v_pk_fma_f32 v[100:101], v[100:101], v[128:129], v[192:193]
	v_pk_fma_f32 v[102:103], v[102:103], v[130:131], v[194:195]
	v_pk_fma_f32 v[112:113], v[112:113], v[128:129], v[204:205]
	v_pk_fma_f32 v[114:115], v[114:115], v[130:131], v[206:207]
	v_pk_fma_f32 v[120:121], v[120:121], v[128:129], v[208:209]
	v_pk_fma_f32 v[122:123], v[122:123], v[130:131], v[210:211]
	v_pk_fma_f32 v[124:125], v[124:125], v[128:129], v[212:213]
	v_pk_fma_f32 v[126:127], v[126:127], v[130:131], v[214:215]
	global_store_dwordx4 v[146:147], v[52:55], off
	global_store_dwordx4 v[144:145], v[72:75], off
	global_store_dwordx4 v[142:143], v[80:83], off
	global_store_dwordx4 v[140:141], v[88:91], off
	global_store_dwordx4 v[138:139], v[100:103], off
	global_store_dwordx4 v[136:137], v[112:115], off
	global_store_dwordx4 v[134:135], v[120:123], off
	global_store_dwordx4 v[132:133], v[124:127], off
	global_load_dwordx4 v[168:171], v[148:149], off offset:512
	global_load_dwordx4 v[172:175], v[150:151], off offset:512
	global_load_dwordx4 v[176:179], v[152:153], off offset:512
	global_load_dwordx4 v[188:191], v[154:155], off offset:512
	global_load_dwordx4 v[192:195], v[156:157], off offset:512
	global_load_dwordx4 v[204:207], v[158:159], off offset:512
	global_load_dwordx4 v[208:211], v[160:161], off offset:512
	global_load_dwordx4 v[212:215], v[162:163], off offset:512
	s_waitcnt vmcnt(16)
	v_pk_fma_f32 v[104:105], v[104:105], v[184:185], v[216:217]
	v_pk_fma_f32 v[106:107], v[106:107], v[186:187], v[218:219]
	v_pk_fma_f32 v[116:117], v[116:117], v[184:185], v[220:221]
	v_pk_fma_f32 v[118:119], v[118:119], v[186:187], v[222:223]
	v_pk_fma_f32 v[108:109], v[108:109], v[184:185], v[228:229]
	v_pk_fma_f32 v[110:111], v[110:111], v[186:187], v[230:231]
	v_pk_fma_f32 v[96:97], v[96:97], v[184:185], v[232:233]
	v_pk_fma_f32 v[98:99], v[98:99], v[186:187], v[234:235]
	v_pk_fma_f32 v[92:93], v[92:93], v[184:185], v[236:237]
	v_pk_fma_f32 v[94:95], v[94:95], v[186:187], v[238:239]
	v_pk_fma_f32 v[84:85], v[84:85], v[184:185], v[240:241]
	v_pk_fma_f32 v[86:87], v[86:87], v[186:187], v[242:243]
	v_pk_fma_f32 v[76:77], v[76:77], v[184:185], v[244:245]
	v_pk_fma_f32 v[78:79], v[78:79], v[186:187], v[246:247]
	v_pk_fma_f32 v[68:69], v[68:69], v[184:185], v[248:249]
	v_pk_fma_f32 v[70:71], v[70:71], v[186:187], v[250:251]
	global_store_dwordx4 v[146:147], v[104:107], off offset:64
	global_store_dwordx4 v[144:145], v[116:119], off offset:64
	global_store_dwordx4 v[142:143], v[108:111], off offset:64
	global_store_dwordx4 v[140:141], v[96:99], off offset:64
	global_store_dwordx4 v[138:139], v[92:95], off offset:64
	global_store_dwordx4 v[136:137], v[84:87], off offset:64
	global_store_dwordx4 v[134:135], v[76:79], off offset:64
	global_store_dwordx4 v[132:133], v[68:71], off offset:64
	global_load_dwordx4 v[216:219], v[148:149], off offset:576
	global_load_dwordx4 v[220:223], v[150:151], off offset:576
	global_load_dwordx4 v[228:231], v[152:153], off offset:576
	global_load_dwordx4 v[232:235], v[154:155], off offset:576
	global_load_dwordx4 v[236:239], v[156:157], off offset:576
	global_load_dwordx4 v[240:243], v[158:159], off offset:576
	global_load_dwordx4 v[244:247], v[160:161], off offset:576
	global_load_dwordx4 v[248:251], v[162:163], off offset:576
	s_waitcnt vmcnt(16)
	v_pk_fma_f32 v[28:29], v[28:29], v[180:181], v[168:169]
	v_pk_fma_f32 v[30:31], v[30:31], v[182:183], v[170:171]
	v_pk_fma_f32 v[36:37], v[36:37], v[180:181], v[172:173]
	v_pk_fma_f32 v[38:39], v[38:39], v[182:183], v[174:175]
	v_pk_fma_f32 v[40:41], v[40:41], v[180:181], v[176:177]
	v_pk_fma_f32 v[42:43], v[42:43], v[182:183], v[178:179]
	v_pk_fma_f32 v[44:45], v[44:45], v[180:181], v[188:189]
	v_pk_fma_f32 v[46:47], v[46:47], v[182:183], v[190:191]
	v_pk_fma_f32 v[48:49], v[48:49], v[180:181], v[192:193]
	v_pk_fma_f32 v[50:51], v[50:51], v[182:183], v[194:195]
	v_pk_fma_f32 v[56:57], v[56:57], v[180:181], v[204:205]
	v_pk_fma_f32 v[58:59], v[58:59], v[182:183], v[206:207]
	v_pk_fma_f32 v[60:61], v[60:61], v[180:181], v[208:209]
	v_pk_fma_f32 v[62:63], v[62:63], v[182:183], v[210:211]
	v_pk_fma_f32 v[64:65], v[64:65], v[180:181], v[212:213]
	v_pk_fma_f32 v[66:67], v[66:67], v[182:183], v[214:215]
	global_store_dwordx4 v[146:147], v[28:31], off offset:512
	global_store_dwordx4 v[144:145], v[36:39], off offset:512
	global_store_dwordx4 v[142:143], v[40:43], off offset:512
	global_store_dwordx4 v[140:141], v[44:47], off offset:512
	global_store_dwordx4 v[138:139], v[48:51], off offset:512
	global_store_dwordx4 v[136:137], v[56:59], off offset:512
	global_store_dwordx4 v[134:135], v[60:63], off offset:512
	global_store_dwordx4 v[132:133], v[64:67], off offset:512
	s_waitcnt vmcnt(8)
	v_pk_fma_f32 v[0:1], v[0:1], v[164:165], v[216:217]
	v_pk_fma_f32 v[2:3], v[2:3], v[166:167], v[218:219]
	v_pk_fma_f32 v[4:5], v[4:5], v[164:165], v[220:221]
	v_pk_fma_f32 v[6:7], v[6:7], v[166:167], v[222:223]
	v_pk_fma_f32 v[8:9], v[8:9], v[164:165], v[228:229]
	v_pk_fma_f32 v[10:11], v[10:11], v[166:167], v[230:231]
	v_pk_fma_f32 v[12:13], v[12:13], v[164:165], v[232:233]
	v_pk_fma_f32 v[14:15], v[14:15], v[166:167], v[234:235]
	v_pk_fma_f32 v[16:17], v[16:17], v[164:165], v[236:237]
	v_pk_fma_f32 v[18:19], v[18:19], v[166:167], v[238:239]
	v_pk_fma_f32 v[20:21], v[20:21], v[164:165], v[240:241]
	v_pk_fma_f32 v[22:23], v[22:23], v[166:167], v[242:243]
	v_pk_fma_f32 v[24:25], v[24:25], v[164:165], v[244:245]
	v_pk_fma_f32 v[26:27], v[26:27], v[166:167], v[246:247]
	v_pk_fma_f32 v[32:33], v[32:33], v[164:165], v[248:249]
	v_pk_fma_f32 v[34:35], v[34:35], v[166:167], v[250:251]
	global_store_dwordx4 v[146:147], v[0:3], off offset:576
	global_store_dwordx4 v[144:145], v[4:7], off offset:576
	global_store_dwordx4 v[142:143], v[8:11], off offset:576
	global_store_dwordx4 v[140:141], v[12:15], off offset:576
	global_store_dwordx4 v[138:139], v[16:19], off offset:576
	global_store_dwordx4 v[136:137], v[20:23], off offset:576
	global_store_dwordx4 v[134:135], v[24:27], off offset:576
	global_store_dwordx4 v[132:133], v[32:35], off offset:576
	v_readlane_b32 s40, v254, 59
